# scan chain loop hand-scheduled: LDS reads hoisted, counted lgkmcnt, in-place state
# speedup vs baseline: 1.0877x; 1.0092x over previous
.LBB0_124:
	s_add_i32 s34, s34, 0xa400
	s_add_i32 s42, s42, 1
	s_add_i32 s43, s43, -1
	s_cmp_eq_u32 s34, 0x148000
	s_cbranch_scc1 .LBB0_118

.LBB0_127:
	s_barrier
	s_mov_b64 s[2:3], -1
	s_and_b64 vcc, s[62:63], exec
	s_cbranch_vccz .LBB0_129
	s_add_i32 s3, s42, -2
	s_mul_i32 s2, s3, 0xab
	s_bfe_u32 s2, s2, 0x70009
	s_mul_i32 s2, s2, 3
	s_sub_i32 s2, s3, s2
	s_and_b32 s2, s2, 0xff
	s_mul_i32 s2, s2, 0xa400
	s_add_i32 s4, s2, s90
	v_add_u32_e32 v8, s4, v60
	v_add_u32_e32 v62, s2, v40
	ds_read2st64_b64 v[12:15], v8 offset0:64 offset1:65
	ds_read2st64_b64 v[16:19], v8 offset0:66 offset1:67
	ds_read_b128 v[94:97], v62 offset:16384
	ds_read_b128 v[102:105], v62 offset:18432
	ds_read_b128 v[110:113], v62 offset:20480
	ds_read_b128 v[118:121], v62 offset:22528
	ds_read_b128 v[98:101], v62 offset:17408
	ds_read_b128 v[106:109], v62 offset:19456
	ds_read_b128 v[114:117], v62 offset:21504
	ds_read_b128 v[122:125], v62 offset:23552
	ds_read_b128 v[126:129], v62
	ds_read_b128 v[130:133], v62 offset:1024
	ds_read_b128 v[134:137], v62 offset:2048
	ds_read_b128 v[138:141], v62 offset:3072
	ds_read_b128 v[142:145], v62 offset:4096
	s_add_i32 s2, s2, s37
	s_and_b64 s[4:5], s[0:1], exec
	s_cselect_b32 s3, s3, s43
	v_lshl_add_u32 v9, v61, 2, s2
	v_lshl_add_u32 v11, s3, 6, v61
	s_add_i32 s2, s2, s36
	v_mov_b32_e32 v10, s2
	s_waitcnt lgkmcnt(13)
	v_lshlrev_b32_e32 v20, 16, v12
	v_and_b32_e32 v21, 0xffff0000, v12
	v_lshlrev_b32_e32 v22, 16, v13
	v_and_b32_e32 v23, 0xffff0000, v13
	v_lshlrev_b32_e32 v24, 16, v14
	v_and_b32_e32 v25, 0xffff0000, v14
	v_lshlrev_b32_e32 v26, 16, v15
	v_and_b32_e32 v27, 0xffff0000, v15
	v_lshlrev_b32_e32 v28, 16, v16
	v_and_b32_e32 v29, 0xffff0000, v16
	v_lshlrev_b32_e32 v30, 16, v17
	v_and_b32_e32 v31, 0xffff0000, v17
	v_lshlrev_b32_e32 v32, 16, v18
	v_and_b32_e32 v33, 0xffff0000, v18
	v_lshlrev_b32_e32 v34, 16, v19
	v_and_b32_e32 v35, 0xffff0000, v19
	s_waitcnt lgkmcnt(9)
	v_mfma_f32_16x16x32_bf16 v[20:23], v[94:97], v[0:3], v[20:23]
	v_mfma_f32_16x16x32_bf16 v[24:27], v[102:105], v[0:3], v[24:27]
	v_mfma_f32_16x16x32_bf16 v[28:31], v[110:113], v[0:3], v[28:31]
	v_mfma_f32_16x16x32_bf16 v[32:35], v[118:121], v[0:3], v[32:35]
	ds_read_b128 v[146:149], v62 offset:5120
	ds_read_b128 v[150:153], v62 offset:6144
	ds_read_b128 v[154:157], v62 offset:7168
	ds_read_b32 v206, v10 offset:40960
	s_waitcnt lgkmcnt(9)
	v_mfma_f32_16x16x32_bf16 v[20:23], v[98:101], v[4:7], v[20:23]
	v_mfma_f32_16x16x32_bf16 v[24:27], v[106:109], v[4:7], v[24:27]
	v_mfma_f32_16x16x32_bf16 v[28:31], v[114:117], v[4:7], v[28:31]
	v_mfma_f32_16x16x32_bf16 v[32:35], v[122:125], v[4:7], v[32:35]
	ds_read_b128 v[190:193], v9 offset:41216
	ds_read_b128 v[194:197], v9 offset:41280
	ds_read_b128 v[198:201], v9 offset:41344
	ds_read_b128 v[202:205], v9 offset:41408
	s_waitcnt lgkmcnt(5)
	ds_read_b128 v[158:161], v62 offset:8192
	ds_read_b128 v[166:169], v62 offset:10240
	ds_read_b128 v[174:177], v62 offset:12288
	ds_read_b128 v[182:185], v62 offset:14336
	v_mfma_f32_16x16x32_bf16 v[36:39], v[126:129], v[0:3], 0
	v_mfma_f32_16x16x32_bf16 v[36:39], v[130:133], v[4:7], v[36:39]
	v_mfma_f32_16x16x32_bf16 v[66:69], v[134:137], v[0:3], 0
	v_mfma_f32_16x16x32_bf16 v[66:69], v[138:141], v[4:7], v[66:69]
	ds_read_b128 v[162:165], v62 offset:9216
	ds_read_b128 v[170:173], v62 offset:11264
	ds_read_b128 v[178:181], v62 offset:13312
	ds_read_b128 v[186:189], v62 offset:15360
	v_mfma_f32_16x16x32_bf16 v[70:73], v[142:145], v[0:3], 0
	v_mfma_f32_16x16x32_bf16 v[70:73], v[146:149], v[4:7], v[70:73]
	v_mfma_f32_16x16x32_bf16 v[74:77], v[150:153], v[0:3], 0
	v_mfma_f32_16x16x32_bf16 v[74:77], v[154:157], v[4:7], v[74:77]
	s_waitcnt lgkmcnt(8)
	v_pk_mul_f32 v[44:45], v[44:45], v[206:207] op_sel_hi:[1,0]
	v_pk_mul_f32 v[46:47], v[46:47], v[206:207] op_sel_hi:[1,0]
	v_pk_mul_f32 v[48:49], v[48:49], v[206:207] op_sel_hi:[1,0]
	v_pk_mul_f32 v[50:51], v[50:51], v[206:207] op_sel_hi:[1,0]
	v_pk_mul_f32 v[52:53], v[52:53], v[206:207] op_sel_hi:[1,0]
	v_pk_mul_f32 v[54:55], v[54:55], v[206:207] op_sel_hi:[1,0]
	v_pk_mul_f32 v[56:57], v[56:57], v[206:207] op_sel_hi:[1,0]
	v_pk_mul_f32 v[58:59], v[58:59], v[206:207] op_sel_hi:[1,0]
	v_cvt_pk_bf16_f32 v78, v20, v21
	v_cvt_pk_bf16_f32 v79, v22, v23
	v_cvt_pk_bf16_f32 v80, v24, v25
	v_cvt_pk_bf16_f32 v81, v26, v27
	v_cvt_pk_bf16_f32 v82, v28, v29
	v_cvt_pk_bf16_f32 v83, v30, v31
	v_cvt_pk_bf16_f32 v84, v32, v33
	v_cvt_pk_bf16_f32 v85, v34, v35
	v_pk_mul_f32 v[20:21], v[20:21], v[190:191]
	v_pk_mul_f32 v[22:23], v[22:23], v[192:193]
	v_pk_mul_f32 v[24:25], v[24:25], v[194:195]
	v_pk_mul_f32 v[26:27], v[26:27], v[196:197]
	v_pk_mul_f32 v[28:29], v[28:29], v[198:199]
	v_pk_mul_f32 v[30:31], v[30:31], v[200:201]
	v_pk_mul_f32 v[32:33], v[32:33], v[202:203]
	v_pk_mul_f32 v[34:35], v[34:35], v[204:205]
	v_cvt_pk_bf16_f32 v86, v20, v21
	v_cvt_pk_bf16_f32 v87, v22, v23
	v_cvt_pk_bf16_f32 v88, v24, v25
	v_cvt_pk_bf16_f32 v89, v26, v27
	v_cvt_pk_bf16_f32 v90, v28, v29
	v_cvt_pk_bf16_f32 v91, v30, v31
	v_cvt_pk_bf16_f32 v92, v32, v33
	v_cvt_pk_bf16_f32 v93, v34, v35
	s_waitcnt lgkmcnt(4)
	v_mfma_f32_16x16x32_bf16 v[44:47], v[158:161], v[86:89], v[44:47]
	v_mfma_f32_16x16x32_bf16 v[48:51], v[166:169], v[86:89], v[48:51]
	v_mfma_f32_16x16x32_bf16 v[52:55], v[174:177], v[86:89], v[52:55]
	v_mfma_f32_16x16x32_bf16 v[56:59], v[182:185], v[86:89], v[56:59]
	ds_read_b128 v[94:97], v62 offset:24576
	ds_read_b128 v[98:101], v62 offset:25600
	ds_read_b128 v[102:105], v62 offset:26624
	ds_read_b128 v[106:109], v62 offset:27648
	s_waitcnt lgkmcnt(4)
	v_mfma_f32_16x16x32_bf16 v[44:47], v[162:165], v[90:93], v[44:47]
	v_mfma_f32_16x16x32_bf16 v[48:51], v[170:173], v[90:93], v[48:51]
	v_mfma_f32_16x16x32_bf16 v[52:55], v[178:181], v[90:93], v[52:55]
	v_mfma_f32_16x16x32_bf16 v[56:59], v[186:189], v[90:93], v[56:59]
	ds_read_b128 v[110:113], v62 offset:28672
	ds_read_b128 v[114:117], v62 offset:29696
	ds_read_b128 v[118:121], v62 offset:30720
	ds_read_b128 v[122:125], v62 offset:31744
	ds_read_b128 v[126:129], v9 offset:40960
	ds_read_b128 v[130:133], v9 offset:41024
	ds_read_b128 v[134:137], v9 offset:41088
	ds_read_b128 v[138:141], v9 offset:41152
	s_waitcnt lgkmcnt(8)
	v_mfma_f32_16x16x32_bf16 v[142:145], v[94:97], v[78:81], 0
	v_mfma_f32_16x16x32_bf16 v[142:145], v[98:101], v[82:85], v[142:145]
	v_mfma_f32_16x16x32_bf16 v[146:149], v[102:105], v[78:81], 0
	v_mfma_f32_16x16x32_bf16 v[146:149], v[106:109], v[82:85], v[146:149]
	v_cvt_pk_bf16_f32 v0, v44, v45
	v_cvt_pk_bf16_f32 v1, v46, v47
	v_cvt_pk_bf16_f32 v2, v48, v49
	v_cvt_pk_bf16_f32 v3, v50, v51
	v_cvt_pk_bf16_f32 v4, v52, v53
	v_cvt_pk_bf16_f32 v5, v54, v55
	v_cvt_pk_bf16_f32 v6, v56, v57
	v_cvt_pk_bf16_f32 v7, v58, v59
	s_waitcnt lgkmcnt(4)
	v_mfma_f32_16x16x32_bf16 v[150:153], v[110:113], v[78:81], 0
	v_mfma_f32_16x16x32_bf16 v[150:153], v[114:117], v[82:85], v[150:153]
	v_mfma_f32_16x16x32_bf16 v[154:157], v[118:121], v[78:81], 0
	v_mfma_f32_16x16x32_bf16 v[154:157], v[122:125], v[82:85], v[154:157]
	v_mad_i64_i32 v[208:209], s[4:5], v11, s39, v[42:43]
	v_add_u32_e32 v62, 16, v11
	v_mad_i64_i32 v[210:211], s[4:5], v62, s39, v[42:43]
	v_add_u32_e32 v62, 32, v11
	v_mad_i64_i32 v[212:213], s[4:5], v62, s39, v[42:43]
	v_add_u32_e32 v62, 48, v11
	v_mad_i64_i32 v[62:63], s[4:5], v62, s39, v[42:43]
	s_waitcnt lgkmcnt(0)
	v_pk_fma_f32 v[36:37], v[36:37], v[126:127], v[142:143]
	v_pk_fma_f32 v[38:39], v[38:39], v[128:129], v[144:145]
	v_pk_fma_f32 v[66:67], v[66:67], v[130:131], v[146:147]
	v_pk_fma_f32 v[68:69], v[68:69], v[132:133], v[148:149]
	v_cvt_pk_bf16_f32 v36, v36, v37
	v_cvt_pk_bf16_f32 v38, v38, v39
	v_cvt_pk_bf16_f32 v66, v66, v67
	v_cvt_pk_bf16_f32 v68, v68, v69
	global_store_short v[208:209], v36, off
	global_store_short_d16_hi v[208:209], v36, off offset:768
	global_store_short v[208:209], v38, off offset:1536
	global_store_short_d16_hi v[208:209], v38, off offset:2304
	global_store_short v[210:211], v66, off
	global_store_short_d16_hi v[210:211], v66, off offset:768
	global_store_short v[210:211], v68, off offset:1536
	global_store_short_d16_hi v[210:211], v68, off offset:2304
	v_pk_fma_f32 v[70:71], v[70:71], v[134:135], v[150:151]
	v_pk_fma_f32 v[72:73], v[72:73], v[136:137], v[152:153]
	v_pk_fma_f32 v[74:75], v[74:75], v[138:139], v[154:155]
	v_pk_fma_f32 v[76:77], v[76:77], v[140:141], v[156:157]
	v_cvt_pk_bf16_f32 v70, v70, v71
	v_cvt_pk_bf16_f32 v72, v72, v73
	v_cvt_pk_bf16_f32 v74, v74, v75
	v_cvt_pk_bf16_f32 v76, v76, v77
	global_store_short v[212:213], v70, off
	global_store_short_d16_hi v[212:213], v70, off offset:768
	global_store_short v[212:213], v72, off offset:1536
	global_store_short_d16_hi v[212:213], v72, off offset:2304
	global_store_short v[62:63], v74, off
	global_store_short_d16_hi v[62:63], v74, off offset:768
	global_store_short v[62:63], v76, off offset:1536
	global_store_short_d16_hi v[62:63], v76, off offset:2304
	s_mov_b64 s[2:3], 0
